# grid barrier: per-XCD release poll back to one load in flight (nothing to drain when the release is seen); the XCD leader no longer drains its outstanding polls before the invalidate
# speedup vs baseline: 1.0231x; 1.0014x over previous
.Lgb258t_out:
.Lgb258_toprel:
	buffer_inv sc1
	s_add_u32 s14, s6, 0x6400
	v_mov_b32_e32 v2, s14
	global_atomic_add v2, v222, s[46:47]
	s_waitcnt vmcnt(0)
	s_branch .Lgb258_done
.Lgb258_local:
	buffer_inv sc1
	s_waitcnt vmcnt(0)
	s_add_u32 s14, s6, 0x6400
	v_mov_b32_e32 v3, s14
	s_mov_b32 s16, 0x40000
.Lgb258l_spin:
	global_load_dword v6, v3, s[46:47] sc1
	s_waitcnt vmcnt(0)
	v_readfirstlane_b32 s17, v6
	s_nop 0
	s_cmp_lg_u32 s17, s7
	s_cbranch_scc1 .Lgb258l_out
	s_sub_u32 s16, s16, 1
	s_cmp_lg_u32 s16, 0
	s_cbranch_scc1 .Lgb258l_spin
